# attention loops: dropped the inline lgkmcnt(0) after the bias-LUT reads where only independent QK MFMAs follow and a later wait guards the first consumer
# baseline (speedup 1.0000x reference)
; #define MFMA32(a, b, c) __builtin_amdgcn_mfma_f32_32x32x16_bf16((a), (b), (c), 0, 0, 0)
; template <int MODE, bool UNI>
; DI void attn_compute(const bf16x8 (&qf)[4], const bf16x8 (&kf)[4], const bf16x8 (&vf)[2][2], int kt, int d00, const float* lut, float ubias, AttnSt& st,
;                      unsigned W, int win, int dmask, bool lane_sel) {
;     ...
;         for (int i = 0; i < 16; ++i) { const int ci = 16 * (i >> 3) + (i & 7); bia[i] = (MODE == 4) ? lb[16 * (23 - ci)] : lb[23 - ci]; }
;     }
;     f32x16 sx;
; #pragma unroll
;     for (int i = 0; i < 16; ++i) sx[i] = 0.f;
; #pragma unroll
;     for (int ks = 0; ks < 4; ++ks) sx = MFMA32(kf[ks], qf[ks], sx);
;     asm volatile("s_waitcnt lgkmcnt(0)" ::: "memory");
;     float sv[16]; float mx = NEGF;
; #pragma unroll
;     for (int i = 0; i < 16; ++i) {
;         const int ci = 16 * (i >> 3) + (i & 7);
;         const int dist = d0 - ci;
;         bool v;
;         if (MODE == 0) v = ((W >> ci) & 1u) != 0u;
;         else if (MODE == 1) v = ((unsigned)dist <= (unsigned)win) && ((dist & dmask) == 0);
;         else if (MODE == 2) v = lane_sel;
;         else v = dist >= 0;
;         const float bias = UNI ? ubias : bia[i];
;         float s = fmaf(sx[i], SC2, bias);
;         if (MODE == 0) { const unsigned t = (unsigned)__builtin_amdgcn_sbfe((int)W, ci, 1);
;             s = __uint_as_float((__float_as_uint(s) & t) | (__float_as_uint(NEGF) & ~t)); }
;         else s = v ? s : NEGF;
;         sv[i] = s; mx = fmaxf(mx, s);
;     }
;     mx = fmaxf(mx, __shfl_xor(mx, 32));
;     const float mnew = fmaxf(st.m, mx);
;     const float msafe = (mnew > -1e29f) ? mnew : 0.f;
;     if (__ballot(mnew > st.m) != 0ull) {
;         const float alpha = __builtin_amdgcn_exp2f(st.m - msafe);
;         st.l *= alpha; st.m = mnew;
; #pragma unroll
;         for (int i = 0; i < 16; ++i) { st.o0[i] *= alpha; st.o1[i] *= alpha; }
;     }
.LBB0_289:
	s_and_b64 vcc, exec, s[46:47]
	s_cbranch_vccz .LBB0_294
	s_waitcnt lgkmcnt(0)
	v_mfma_f32_32x32x16_bf16 v[34:49], v[106:109], v[78:81], 0
	ds_read2_b32 v[50:51], v0 offset0:22 offset1:23
	ds_read2_b32 v[52:53], v0 offset0:20 offset1:21
	ds_read2_b32 v[54:55], v0 offset0:18 offset1:19
	ds_read2_b32 v[56:57], v0 offset0:16 offset1:17
	v_add_u32_e32 v106, 0x98, v151
	v_cmp_gt_u32_e32 vcc, s95, v106
	v_add_u32_e32 v107, 18, v151
	ds_read2_b32 v[58:59], v0 offset0:6 offset1:7
	ds_read2_b32 v[60:61], v0 offset0:4 offset1:5
	ds_read2_b32 v[62:63], v0 offset0:2 offset1:3
	ds_read2_b32 v[64:65], v0 offset1:1
	v_mfma_f32_32x32x16_bf16 v[34:49], v[110:113], v[74:77], v[34:49]
	v_mfma_f32_32x32x16_bf16 v[34:49], v[102:105], v[70:73], v[34:49]
	v_add_u32_e32 v102, 22, v151
	v_add_u32_e32 v103, 21, v151
	v_add_u32_e32 v104, 20, v151
	v_add_u32_e32 v105, 19, v151
	v_mfma_f32_32x32x16_bf16 v[34:49], v[98:101], v[66:69], v[34:49]
	s_waitcnt lgkmcnt(0)
	s_nop 10
	v_fmamk_f32 v34, v34, 0x3e38aa3b, v51
	v_fmac_f32_e32 v50, 0x3e38aa3b, v35
	v_cndmask_b32_e32 v35, v239, v34, vcc
	v_cmp_lt_u32_e32 vcc, s13, v102
	v_fmamk_f32 v51, v36, 0x3e38aa3b, v53
	v_fmac_f32_e32 v52, 0x3e38aa3b, v37
	v_cndmask_b32_e32 v36, v239, v50, vcc
	v_cmp_lt_u32_e32 vcc, s13, v103
	v_fmamk_f32 v38, v38, 0x3e38aa3b, v55
	v_fmac_f32_e32 v54, 0x3e38aa3b, v39
	v_cndmask_b32_e32 v37, v239, v51, vcc
	v_cmp_lt_u32_e32 vcc, s13, v104
	v_add_u32_e32 v51, 17, v151
	v_fmamk_f32 v40, v40, 0x3e38aa3b, v57
	v_cndmask_b32_e32 v34, v239, v52, vcc
	v_cmp_lt_u32_e32 vcc, s13, v105
	v_fmac_f32_e32 v56, 0x3e38aa3b, v41
	v_fmamk_f32 v42, v42, 0x3e38aa3b, v59
	v_cndmask_b32_e32 v39, v239, v38, vcc
	v_cmp_lt_u32_e32 vcc, s13, v107
	v_max3_f32 v38, v35, s30, v36
	v_fmac_f32_e32 v58, 0x3e38aa3b, v43
	v_cndmask_b32_e32 v50, v239, v54, vcc
	v_cmp_lt_u32_e32 vcc, s13, v51
	v_max3_f32 v38, v38, v37, v34
	v_fmamk_f32 v44, v44, 0x3e38aa3b, v61
	v_cndmask_b32_e32 v51, v239, v40, vcc
	v_add_u32_e32 v40, 16, v151
	v_cmp_lt_u32_e32 vcc, s13, v40
	v_add_u32_e32 v40, 7, v151
	v_max3_f32 v38, v38, v39, v50
	v_cndmask_b32_e32 v41, v239, v56, vcc
	v_cmp_lt_u32_e32 vcc, s13, v40
	v_add_u32_e32 v40, 6, v151
	v_fmac_f32_e32 v60, 0x3e38aa3b, v45
	v_cndmask_b32_e32 v42, v239, v42, vcc
	v_cmp_lt_u32_e32 vcc, s13, v40
	v_add_u32_e32 v40, 5, v151
	v_max3_f32 v38, v38, v51, v41
	v_cndmask_b32_e32 v43, v239, v58, vcc
	v_cmp_lt_u32_e32 vcc, s13, v40
	v_add_u32_e32 v40, 4, v151
	v_fmamk_f32 v46, v46, 0x3e38aa3b, v63
	v_cndmask_b32_e32 v44, v239, v44, vcc
	v_cmp_lt_u32_e32 vcc, s13, v40
	v_add_u32_e32 v40, 3, v151
	v_max3_f32 v38, v38, v42, v43
	v_cndmask_b32_e32 v45, v239, v60, vcc
	v_cmp_lt_u32_e32 vcc, s13, v40
	v_add_u32_e32 v40, 2, v151
	v_fmac_f32_e32 v62, 0x3e38aa3b, v47
	v_cndmask_b32_e32 v46, v239, v46, vcc
	v_cmp_lt_u32_e32 vcc, s13, v40
	v_max3_f32 v38, v38, v44, v45
	v_fmamk_f32 v48, v48, 0x3e38aa3b, v65
	v_cndmask_b32_e32 v47, v239, v62, vcc
	v_max3_f32 v40, v38, v46, v47
	v_add_u32_e32 v38, 1, v151
	v_cmp_lt_u32_e32 vcc, s13, v38
	v_fmac_f32_e32 v64, 0x3e38aa3b, v49
	s_nop 0
	v_cndmask_b32_e32 v48, v239, v48, vcc
	v_cmp_lt_u32_e32 vcc, s13, v151
	s_nop 1
	v_cndmask_b32_e32 v38, v239, v64, vcc
	v_max3_f32 v40, v40, v48, v38
	v_mov_b32_e32 v49, v40
	s_nop 1
	v_permlane32_swap_b32_e32 v49, v40
	s_waitcnt lgkmcnt(0)
	v_max3_f32 v169, v153, v40, v49
	v_cmp_lt_f32_e32 vcc, s12, v169
	s_nop 1
	v_cndmask_b32_e32 v40, 0, v169, vcc
	v_cmp_gt_f32_e32 vcc, v169, v153
	s_cbranch_vccz .LBB0_292
	v_sub_f32_e32 v49, v153, v40
	v_exp_f32_e32 v52, v49
	s_nop 0
	v_mul_f32_e32 v150, v150, v52
	v_pk_mul_f32 v[16:17], v[16:17], v[52:53] op_sel_hi:[1,0]
	v_pk_mul_f32 v[14:15], v[14:15], v[52:53] op_sel_hi:[1,0]
	v_pk_mul_f32 v[12:13], v[12:13], v[52:53] op_sel_hi:[1,0]
	v_pk_mul_f32 v[10:11], v[10:11], v[52:53] op_sel_hi:[1,0]
	v_pk_mul_f32 v[8:9], v[8:9], v[52:53] op_sel_hi:[1,0]
	v_pk_mul_f32 v[6:7], v[6:7], v[52:53] op_sel_hi:[1,0]
	v_pk_mul_f32 v[4:5], v[4:5], v[52:53] op_sel_hi:[1,0]
	v_pk_mul_f32 v[2:3], v[2:3], v[52:53] op_sel_hi:[1,0]
	v_pk_mul_f32 v[32:33], v[32:33], v[52:53] op_sel_hi:[1,0]
	v_pk_mul_f32 v[30:31], v[30:31], v[52:53] op_sel_hi:[1,0]
	v_pk_mul_f32 v[28:29], v[28:29], v[52:53] op_sel_hi:[1,0]
	v_pk_mul_f32 v[26:27], v[26:27], v[52:53] op_sel_hi:[1,0]
	v_pk_mul_f32 v[24:25], v[24:25], v[52:53] op_sel_hi:[1,0]
	v_pk_mul_f32 v[22:23], v[22:23], v[52:53] op_sel_hi:[1,0]
	v_pk_mul_f32 v[20:21], v[20:21], v[52:53] op_sel_hi:[1,0]
	v_pk_mul_f32 v[18:19], v[18:19], v[52:53] op_sel_hi:[1,0]
	s_branch .LBB0_293

; #define MFMA32(a, b, c) __builtin_amdgcn_mfma_f32_32x32x16_bf16((a), (b), (c), 0, 0, 0)
; template <int MODE, bool UNI>
; DI void attn_compute(const bf16x8 (&qf)[4], const bf16x8 (&kf)[4], const bf16x8 (&vf)[2][2], int kt, int d00, const float* lut, float ubias, AttnSt& st,
;                      unsigned W, int win, int dmask, bool lane_sel) {
;     ...
;         for (int i = 0; i < 16; ++i) { const int ci = 16 * (i >> 3) + (i & 7); bia[i] = (MODE == 4) ? lb[16 * (23 - ci)] : lb[23 - ci]; }
;     }
;     f32x16 sx;
; #pragma unroll
;     for (int i = 0; i < 16; ++i) sx[i] = 0.f;
; #pragma unroll
;     for (int ks = 0; ks < 4; ++ks) sx = MFMA32(kf[ks], qf[ks], sx);
;     asm volatile("s_waitcnt lgkmcnt(0)" ::: "memory");
;     float sv[16]; float mx = NEGF;
; #pragma unroll
;     for (int i = 0; i < 16; ++i) {
;         const int ci = 16 * (i >> 3) + (i & 7);
;         const int dist = d0 - ci;
;         bool v;
;         if (MODE == 0) v = ((W >> ci) & 1u) != 0u;
;         else if (MODE == 1) v = ((unsigned)dist <= (unsigned)win) && ((dist & dmask) == 0);
;         else if (MODE == 2) v = lane_sel;
;         else v = dist >= 0;
;         const float bias = UNI ? ubias : bia[i];
;         float s = fmaf(sx[i], SC2, bias);
;         if (MODE == 0) { const unsigned t = (unsigned)__builtin_amdgcn_sbfe((int)W, ci, 1);
;             s = __uint_as_float((__float_as_uint(s) & t) | (__float_as_uint(NEGF) & ~t)); }
;         else s = v ? s : NEGF;
;         sv[i] = s; mx = fmaxf(mx, s);
;     }
;     mx = fmaxf(mx, __shfl_xor(mx, 32));
;     const float mnew = fmaxf(st.m, mx);
;     const float msafe = (mnew > -1e29f) ? mnew : 0.f;
;     if (__ballot(mnew > st.m) != 0ull) {
;         const float alpha = __builtin_amdgcn_exp2f(st.m - msafe);
;         st.l *= alpha; st.m = mnew;
; #pragma unroll
;         for (int i = 0; i < 16; ++i) { st.o0[i] *= alpha; st.o1[i] *= alpha; }
;     }
.LBB0_308:
	s_and_b64 vcc, exec, s[46:47]
	s_cbranch_vccz .LBB0_313
	s_waitcnt lgkmcnt(0)
	v_mfma_f32_32x32x16_bf16 v[2:17], v[106:109], v[78:81], 0
	ds_read2_b32 v[50:51], v169 offset0:22 offset1:23
	ds_read2_b32 v[52:53], v169 offset0:20 offset1:21
	ds_read2_b32 v[54:55], v169 offset0:18 offset1:19
	ds_read2_b32 v[56:57], v169 offset0:16 offset1:17
	v_add_u32_e32 v106, 0x98, v170
	v_cmp_gt_u32_e32 vcc, s95, v106
	v_add_u32_e32 v107, 18, v170
	ds_read2_b32 v[58:59], v169 offset0:6 offset1:7
	ds_read2_b32 v[60:61], v169 offset0:4 offset1:5
	ds_read2_b32 v[62:63], v169 offset0:2 offset1:3
	ds_read2_b32 v[64:65], v169 offset1:1
	v_mfma_f32_32x32x16_bf16 v[2:17], v[110:113], v[74:77], v[2:17]
	v_mfma_f32_32x32x16_bf16 v[2:17], v[102:105], v[70:73], v[2:17]
	v_add_u32_e32 v102, 22, v170
	v_add_u32_e32 v103, 21, v170
	v_add_u32_e32 v104, 20, v170
	v_add_u32_e32 v105, 19, v170
	v_mfma_f32_32x32x16_bf16 v[2:17], v[98:101], v[66:69], v[2:17]
	s_waitcnt lgkmcnt(0)
	s_nop 10
	v_fmamk_f32 v2, v2, 0x3e38aa3b, v51
	v_fmac_f32_e32 v50, 0x3e38aa3b, v3
	v_cndmask_b32_e32 v3, v239, v2, vcc
	v_cmp_lt_u32_e32 vcc, s13, v102
	v_fmamk_f32 v51, v4, 0x3e38aa3b, v53
	v_fmac_f32_e32 v52, 0x3e38aa3b, v5
	v_cndmask_b32_e32 v4, v239, v50, vcc
	v_cmp_lt_u32_e32 vcc, s13, v103
	v_fmamk_f32 v6, v6, 0x3e38aa3b, v55
	v_fmac_f32_e32 v54, 0x3e38aa3b, v7
	v_cndmask_b32_e32 v5, v239, v51, vcc
	v_cmp_lt_u32_e32 vcc, s13, v104
	v_add_u32_e32 v51, 17, v170
	v_fmamk_f32 v8, v8, 0x3e38aa3b, v57
	v_cndmask_b32_e32 v2, v239, v52, vcc
	v_cmp_lt_u32_e32 vcc, s13, v105
	v_fmac_f32_e32 v56, 0x3e38aa3b, v9
	v_fmamk_f32 v10, v10, 0x3e38aa3b, v59
	v_cndmask_b32_e32 v7, v239, v6, vcc
	v_cmp_lt_u32_e32 vcc, s13, v107
	v_max3_f32 v6, v3, s30, v4
	v_fmac_f32_e32 v58, 0x3e38aa3b, v11
	v_cndmask_b32_e32 v50, v239, v54, vcc
	v_cmp_lt_u32_e32 vcc, s13, v51
	v_max3_f32 v6, v6, v5, v2
	v_fmamk_f32 v12, v12, 0x3e38aa3b, v61
	v_cndmask_b32_e32 v51, v239, v8, vcc
	v_add_u32_e32 v8, 16, v170
	v_cmp_lt_u32_e32 vcc, s13, v8
	v_add_u32_e32 v8, 7, v170
	v_max3_f32 v6, v6, v7, v50
	v_cndmask_b32_e32 v9, v239, v56, vcc
	v_cmp_lt_u32_e32 vcc, s13, v8
	v_add_u32_e32 v8, 6, v170
	v_fmac_f32_e32 v60, 0x3e38aa3b, v13
	v_cndmask_b32_e32 v10, v239, v10, vcc
	v_cmp_lt_u32_e32 vcc, s13, v8
	v_add_u32_e32 v8, 5, v170
	v_max3_f32 v6, v6, v51, v9
	v_cndmask_b32_e32 v11, v239, v58, vcc
	v_cmp_lt_u32_e32 vcc, s13, v8
	v_add_u32_e32 v8, 4, v170
	v_fmamk_f32 v14, v14, 0x3e38aa3b, v63
	v_cndmask_b32_e32 v12, v239, v12, vcc
	v_cmp_lt_u32_e32 vcc, s13, v8
	v_add_u32_e32 v8, 3, v170
	v_max3_f32 v6, v6, v10, v11
	v_cndmask_b32_e32 v13, v239, v60, vcc
	v_cmp_lt_u32_e32 vcc, s13, v8
	v_add_u32_e32 v8, 2, v170
	v_fmac_f32_e32 v62, 0x3e38aa3b, v15
	v_cndmask_b32_e32 v14, v239, v14, vcc
	v_cmp_lt_u32_e32 vcc, s13, v8
	v_max3_f32 v6, v6, v12, v13
	v_fmamk_f32 v16, v16, 0x3e38aa3b, v65
	v_cndmask_b32_e32 v15, v239, v62, vcc
	v_max3_f32 v8, v6, v14, v15
	v_add_u32_e32 v6, 1, v170
	v_cmp_lt_u32_e32 vcc, s13, v6
	v_fmac_f32_e32 v64, 0x3e38aa3b, v17
	s_nop 0
	v_cndmask_b32_e32 v16, v239, v16, vcc
	v_cmp_lt_u32_e32 vcc, s13, v170
	s_nop 1
	v_cndmask_b32_e32 v6, v239, v64, vcc
	v_max3_f32 v8, v8, v16, v6
	v_mov_b32_e32 v17, v8
	s_nop 1
	v_permlane32_swap_b32_e32 v17, v8
	s_waitcnt lgkmcnt(0)
	v_max3_f32 v173, v172, v8, v17
	v_cmp_lt_f32_e32 vcc, s12, v173
	s_nop 1
	v_cndmask_b32_e32 v8, 0, v173, vcc
	v_cmp_gt_f32_e32 vcc, v173, v172
	s_cbranch_vccz .LBB0_311
	v_sub_f32_e32 v17, v172, v8
	v_exp_f32_e32 v52, v17
	s_nop 0
	v_mul_f32_e32 v149, v149, v52
	v_pk_mul_f32 v[48:49], v[48:49], v[52:53] op_sel_hi:[1,0]
	v_pk_mul_f32 v[46:47], v[46:47], v[52:53] op_sel_hi:[1,0]
	v_pk_mul_f32 v[44:45], v[44:45], v[52:53] op_sel_hi:[1,0]
	v_pk_mul_f32 v[42:43], v[42:43], v[52:53] op_sel_hi:[1,0]
	v_pk_mul_f32 v[40:41], v[40:41], v[52:53] op_sel_hi:[1,0]
	v_pk_mul_f32 v[38:39], v[38:39], v[52:53] op_sel_hi:[1,0]
	v_pk_mul_f32 v[36:37], v[36:37], v[52:53] op_sel_hi:[1,0]
	v_pk_mul_f32 v[34:35], v[34:35], v[52:53] op_sel_hi:[1,0]
	v_pk_mul_f32 v[32:33], v[32:33], v[52:53] op_sel_hi:[1,0]
	v_pk_mul_f32 v[30:31], v[30:31], v[52:53] op_sel_hi:[1,0]
	v_pk_mul_f32 v[28:29], v[28:29], v[52:53] op_sel_hi:[1,0]
	v_pk_mul_f32 v[26:27], v[26:27], v[52:53] op_sel_hi:[1,0]
	v_pk_mul_f32 v[24:25], v[24:25], v[52:53] op_sel_hi:[1,0]
	v_pk_mul_f32 v[22:23], v[22:23], v[52:53] op_sel_hi:[1,0]
	v_pk_mul_f32 v[20:21], v[20:21], v[52:53] op_sel_hi:[1,0]
	v_pk_mul_f32 v[18:19], v[18:19], v[52:53] op_sel_hi:[1,0]
	s_branch .LBB0_312

; #define MFMA32(a, b, c) __builtin_amdgcn_mfma_f32_32x32x16_bf16((a), (b), (c), 0, 0, 0)
; template <int MODE, bool UNI>
; DI void attn_compute(const bf16x8 (&qf)[4], const bf16x8 (&kf)[4], const bf16x8 (&vf)[2][2], int kt, int d00, const float* lut, float ubias, AttnSt& st,
;                      unsigned W, int win, int dmask, bool lane_sel) {
;     ...
;         for (int i = 0; i < 16; ++i) { const int ci = 16 * (i >> 3) + (i & 7); bia[i] = (MODE == 4) ? lb[16 * (23 - ci)] : lb[23 - ci]; }
;     }
;     f32x16 sx;
; #pragma unroll
;     for (int i = 0; i < 16; ++i) sx[i] = 0.f;
; #pragma unroll
;     for (int ks = 0; ks < 4; ++ks) sx = MFMA32(kf[ks], qf[ks], sx);
;     asm volatile("s_waitcnt lgkmcnt(0)" ::: "memory");
;     float sv[16]; float mx = NEGF;
; #pragma unroll
;     for (int i = 0; i < 16; ++i) {
;         const int ci = 16 * (i >> 3) + (i & 7);
;         const int dist = d0 - ci;
;         bool v;
;         if (MODE == 0) v = ((W >> ci) & 1u) != 0u;
;         else if (MODE == 1) v = ((unsigned)dist <= (unsigned)win) && ((dist & dmask) == 0);
;         else if (MODE == 2) v = lane_sel;
;         else v = dist >= 0;
;         const float bias = UNI ? ubias : bia[i];
;         float s = fmaf(sx[i], SC2, bias);
;         if (MODE == 0) { const unsigned t = (unsigned)__builtin_amdgcn_sbfe((int)W, ci, 1);
;             s = __uint_as_float((__float_as_uint(s) & t) | (__float_as_uint(NEGF) & ~t)); }
;         else s = v ? s : NEGF;
;         sv[i] = s; mx = fmaxf(mx, s);
;     }
;     mx = fmaxf(mx, __shfl_xor(mx, 32));
;     const float mnew = fmaxf(st.m, mx);
;     const float msafe = (mnew > -1e29f) ? mnew : 0.f;
;     if (__ballot(mnew > st.m) != 0ull) {
;         const float alpha = __builtin_amdgcn_exp2f(st.m - msafe);
;         st.l *= alpha; st.m = mnew;
; #pragma unroll
;         for (int i = 0; i < 16; ++i) { st.o0[i] *= alpha; st.o1[i] *= alpha; }
;     }
.LBB0_324:
	s_waitcnt lgkmcnt(0)
	v_mfma_f32_32x32x16_bf16 v[34:49], v[34:37], v[62:65], 0
	v_lshrrev_b32_e32 v150, v137, v106
	v_bfe_i32 v151, v150, 4, 1
	v_bfe_i32 v152, v150, 5, 1
	v_bfe_i32 v153, v150, 6, 1
	v_mfma_f32_32x32x16_bf16 v[34:49], v[90:93], v[58:61], v[34:49]
	ds_read2_b32 v[90:91], v103 offset0:22 offset1:23
	ds_read2_b32 v[92:93], v103 offset0:20 offset1:21
	ds_read2_b32 v[106:107], v103 offset0:18 offset1:19
	ds_read2_b32 v[108:109], v103 offset0:16 offset1:17
	ds_read2_b32 v[110:111], v103 offset0:6 offset1:7
	ds_read2_b32 v[112:113], v103 offset0:4 offset1:5
	ds_read2_b32 v[146:147], v103 offset0:2 offset1:3
	ds_read2_b32 v[148:149], v103 offset1:1
	v_mfma_f32_32x32x16_bf16 v[34:49], v[86:89], v[54:57], v[34:49]
	v_bfe_i32 v88, v150, 2, 1
	v_bfe_i32 v86, v150, 0, 1
	v_bfe_i32 v87, v150, 1, 1
	v_bfe_i32 v89, v150, 3, 1
	v_mfma_f32_32x32x16_bf16 v[34:49], v[82:85], v[50:53], v[34:49]
	s_waitcnt lgkmcnt(0)
	s_nop 10
	v_fmac_f32_e32 v90, 0x3e38aa3b, v35
	v_fmamk_f32 v35, v36, 0x3e38aa3b, v93
	v_fmamk_f32 v36, v38, 0x3e38aa3b, v107
	v_bitop3_b32 v83, v35, s30, v88 bitop3:0xe4
	v_fmac_f32_e32 v108, 0x3e38aa3b, v41
	v_bfe_i32 v35, v150, 7, 1
	v_fmamk_f32 v34, v34, 0x3e38aa3b, v91
	v_fmac_f32_e32 v92, 0x3e38aa3b, v37
	v_fmac_f32_e32 v106, 0x3e38aa3b, v39
	v_fmamk_f32 v37, v40, 0x3e38aa3b, v109
	v_bitop3_b32 v39, v36, s30, v151 bitop3:0xe4
	v_bitop3_b32 v40, v108, s30, v35 bitop3:0xe4
	v_fmamk_f32 v35, v42, 0x3e38aa3b, v111
	v_bfe_i32 v36, v150, 16, 1
	v_bitop3_b32 v85, v34, s30, v86 bitop3:0xe4
	v_bitop3_b32 v84, v90, s30, v87 bitop3:0xe4
	v_bitop3_b32 v41, v35, s30, v36 bitop3:0xe4
	v_fmac_f32_e32 v110, 0x3e38aa3b, v43
	v_bfe_i32 v35, v150, 17, 1
	v_bitop3_b32 v82, v92, s30, v89 bitop3:0xe4
	v_max3_f32 v34, v85, s30, v84
	v_bitop3_b32 v42, v110, s30, v35 bitop3:0xe4
	v_fmamk_f32 v35, v44, 0x3e38aa3b, v113
	v_bfe_i32 v36, v150, 18, 1
	v_bitop3_b32 v38, v106, s30, v152 bitop3:0xe4
	v_max3_f32 v34, v34, v83, v82
	v_bitop3_b32 v43, v35, s30, v36 bitop3:0xe4
	v_fmac_f32_e32 v112, 0x3e38aa3b, v45
	v_bfe_i32 v35, v150, 19, 1
	v_bitop3_b32 v37, v37, s30, v153 bitop3:0xe4
	v_max3_f32 v34, v34, v39, v38
	v_bitop3_b32 v44, v112, s30, v35 bitop3:0xe4
	v_fmamk_f32 v35, v46, 0x3e38aa3b, v147
	v_bfe_i32 v36, v150, 20, 1
	v_max3_f32 v34, v34, v37, v40
	v_bitop3_b32 v45, v35, s30, v36 bitop3:0xe4
	v_fmac_f32_e32 v146, 0x3e38aa3b, v47
	v_bfe_i32 v35, v150, 21, 1
	v_max3_f32 v34, v34, v41, v42
	v_bitop3_b32 v46, v146, s30, v35 bitop3:0xe4
	v_fmamk_f32 v35, v48, 0x3e38aa3b, v149
	v_bfe_i32 v36, v150, 22, 1
	v_max3_f32 v34, v34, v43, v44
	v_bitop3_b32 v47, v35, s30, v36 bitop3:0xe4
	v_fmac_f32_e32 v148, 0x3e38aa3b, v49
	v_bfe_i32 v35, v150, 23, 1
	v_max3_f32 v34, v34, v45, v46
	v_bitop3_b32 v35, v148, s30, v35 bitop3:0xe4
	v_max3_f32 v34, v34, v47, v35
	v_mov_b32_e32 v36, v34
	s_nop 1
	v_permlane32_swap_b32_e32 v36, v34
	s_waitcnt lgkmcnt(0)
	v_max3_f32 v34, v105, v34, v36
	v_cmp_lt_f32_e32 vcc, s12, v34
	s_nop 1
	v_cndmask_b32_e32 v36, 0, v34, vcc
	v_cmp_gt_f32_e32 vcc, v34, v105
	s_cbranch_vccz .LBB0_326
	v_sub_f32_e32 v48, v105, v36
	v_exp_f32_e32 v48, v48
	s_nop 0
	v_mul_f32_e32 v102, v102, v48
	v_pk_mul_f32 v[32:33], v[32:33], v[48:49] op_sel_hi:[1,0]
	v_pk_mul_f32 v[30:31], v[30:31], v[48:49] op_sel_hi:[1,0]
	v_pk_mul_f32 v[28:29], v[28:29], v[48:49] op_sel_hi:[1,0]
	v_pk_mul_f32 v[26:27], v[26:27], v[48:49] op_sel_hi:[1,0]
	v_pk_mul_f32 v[24:25], v[24:25], v[48:49] op_sel_hi:[1,0]
	v_pk_mul_f32 v[22:23], v[22:23], v[48:49] op_sel_hi:[1,0]
	v_pk_mul_f32 v[20:21], v[20:21], v[48:49] op_sel_hi:[1,0]
	v_pk_mul_f32 v[18:19], v[18:19], v[48:49] op_sel_hi:[1,0]
	v_pk_mul_f32 v[16:17], v[16:17], v[48:49] op_sel_hi:[1,0]
	v_pk_mul_f32 v[14:15], v[14:15], v[48:49] op_sel_hi:[1,0]
	v_pk_mul_f32 v[12:13], v[12:13], v[48:49] op_sel_hi:[1,0]
	v_pk_mul_f32 v[10:11], v[10:11], v[48:49] op_sel_hi:[1,0]
	v_pk_mul_f32 v[8:9], v[8:9], v[48:49] op_sel_hi:[1,0]
	v_pk_mul_f32 v[6:7], v[6:7], v[48:49] op_sel_hi:[1,0]
	v_pk_mul_f32 v[4:5], v[4:5], v[48:49] op_sel_hi:[1,0]
	v_pk_mul_f32 v[2:3], v[2:3], v[48:49] op_sel_hi:[1,0]
	s_branch .LBB0_327

; #define MFMA32(a, b, c) __builtin_amdgcn_mfma_f32_32x32x16_bf16((a), (b), (c), 0, 0, 0)
; template <int MODE, bool UNI>
; DI void attn_compute(const bf16x8 (&qf)[4], const bf16x8 (&kf)[4], const bf16x8 (&vf)[2][2], int kt, int d00, const float* lut, float ubias, AttnSt& st,
;                      unsigned W, int win, int dmask, bool lane_sel) {
;     ...
;         for (int i = 0; i < 16; ++i) { const int ci = 16 * (i >> 3) + (i & 7); bia[i] = (MODE == 4) ? lb[16 * (23 - ci)] : lb[23 - ci]; }
;     }
;     f32x16 sx;
; #pragma unroll
;     for (int i = 0; i < 16; ++i) sx[i] = 0.f;
; #pragma unroll
;     for (int ks = 0; ks < 4; ++ks) sx = MFMA32(kf[ks], qf[ks], sx);
;     asm volatile("s_waitcnt lgkmcnt(0)" ::: "memory");
;     float sv[16]; float mx = NEGF;
; #pragma unroll
;     for (int i = 0; i < 16; ++i) {
;         const int ci = 16 * (i >> 3) + (i & 7);
;         const int dist = d0 - ci;
;         bool v;
;         if (MODE == 0) v = ((W >> ci) & 1u) != 0u;
;         else if (MODE == 1) v = ((unsigned)dist <= (unsigned)win) && ((dist & dmask) == 0);
;         else if (MODE == 2) v = lane_sel;
;         else v = dist >= 0;
;         const float bias = UNI ? ubias : bia[i];
;         float s = fmaf(sx[i], SC2, bias);
;         if (MODE == 0) { const unsigned t = (unsigned)__builtin_amdgcn_sbfe((int)W, ci, 1);
;             s = __uint_as_float((__float_as_uint(s) & t) | (__float_as_uint(NEGF) & ~t)); }
;         else s = v ? s : NEGF;
;         sv[i] = s; mx = fmaxf(mx, s);
;     }
;     mx = fmaxf(mx, __shfl_xor(mx, 32));
;     const float mnew = fmaxf(st.m, mx);
;     const float msafe = (mnew > -1e29f) ? mnew : 0.f;
;     if (__ballot(mnew > st.m) != 0ull) {
;         const float alpha = __builtin_amdgcn_exp2f(st.m - msafe);
;         st.l *= alpha; st.m = mnew;
; #pragma unroll
;         for (int i = 0; i < 16; ++i) { st.o0[i] *= alpha; st.o1[i] *= alpha; }
;     }
.LBB0_349:
	s_waitcnt lgkmcnt(0)
	v_mfma_f32_32x32x16_bf16 v[50:65], v[50:53], v[70:73], 0
	v_add_u32_e32 v0, s65, v105
	v_mfma_f32_32x32x16_bf16 v[50:65], v[90:93], v[66:69], v[50:65]
	v_mfma_f32_32x32x16_bf16 v[50:65], v[94:97], v[78:81], v[50:65]
	ds_read2_b32 v[14:15], v0 offset0:22 offset1:23
	ds_read2_b32 v[90:91], v0 offset0:20 offset1:21
	ds_read2_b32 v[92:93], v0 offset0:18 offset1:19
	ds_read2_b32 v[94:95], v0 offset0:16 offset1:17
	ds_read2_b32 v[96:97], v0 offset0:6 offset1:7
	ds_read2_b32 v[108:109], v0 offset0:4 offset1:5
	ds_read2_b32 v[110:111], v0 offset0:2 offset1:3
	ds_read2_b32 v[112:113], v0 offset1:1
	v_mfma_f32_32x32x16_bf16 v[50:65], v[86:89], v[74:77], v[50:65]
	s_waitcnt lgkmcnt(0)
	s_nop 10
	v_fmamk_f32 v0, v50, 0x3e38aa3b, v15
	v_fmac_f32_e32 v14, 0x3e38aa3b, v51
	v_fmamk_f32 v15, v52, 0x3e38aa3b, v91
	v_fmac_f32_e32 v90, 0x3e38aa3b, v53
	v_cndmask_b32_e64 v89, v239, v0, s[0:1]
	v_cndmask_b32_e64 v88, v239, v14, s[0:1]
	v_fmamk_f32 v50, v54, 0x3e38aa3b, v93
	v_fmac_f32_e32 v92, 0x3e38aa3b, v55
	v_cndmask_b32_e64 v87, v239, v15, s[0:1]
	v_cndmask_b32_e64 v86, v239, v90, s[0:1]
	v_max3_f32 v0, v89, s30, v88
	v_fmamk_f32 v51, v56, 0x3e38aa3b, v95
	v_fmac_f32_e32 v94, 0x3e38aa3b, v57
	v_fmac_f32_e32 v96, 0x3e38aa3b, v59
	v_fmamk_f32 v53, v60, 0x3e38aa3b, v109
	v_cndmask_b32_e64 v60, v239, v50, s[0:1]
	v_cndmask_b32_e64 v59, v239, v92, s[0:1]
	v_max3_f32 v0, v0, v87, v86
	v_fmamk_f32 v52, v58, 0x3e38aa3b, v97
	v_cndmask_b32_e64 v58, v239, v51, s[0:1]
	v_cndmask_b32_e64 v57, v239, v94, s[0:1]
	v_max3_f32 v0, v0, v60, v59
	v_cndmask_b32_e64 v51, v239, v52, s[0:1]
	v_cndmask_b32_e64 v50, v239, v96, s[0:1]
	v_max3_f32 v0, v0, v58, v57
	v_fmac_f32_e32 v108, 0x3e38aa3b, v61
	v_max3_f32 v0, v0, v51, v50
	v_cndmask_b32_e64 v52, v239, v53, s[0:1]
	v_cndmask_b32_e64 v53, v239, v108, s[0:1]
	v_fmamk_f32 v14, v62, 0x3e38aa3b, v111
	v_fmac_f32_e32 v110, 0x3e38aa3b, v63
	v_max3_f32 v0, v0, v52, v53
	v_cndmask_b32_e64 v54, v239, v14, s[0:1]
	v_cndmask_b32_e64 v55, v239, v110, s[0:1]
	v_fmamk_f32 v14, v64, 0x3e38aa3b, v113
	v_fmac_f32_e32 v112, 0x3e38aa3b, v65
	v_max3_f32 v0, v0, v54, v55
	v_cndmask_b32_e64 v56, v239, v14, s[0:1]
	v_cndmask_b32_e64 v14, v239, v112, s[0:1]
	v_max3_f32 v0, v0, v56, v14
	v_mov_b32_e32 v15, v0
	s_nop 1
	v_permlane32_swap_b32_e32 v15, v0
	s_waitcnt lgkmcnt(0)
	v_max3_f32 v0, v106, v0, v15
	v_cmp_lt_f32_e32 vcc, s12, v0
	s_nop 1
	v_cndmask_b32_e32 v15, 0, v0, vcc
	v_cmp_gt_f32_e32 vcc, v0, v106
	s_cbranch_vccz .LBB0_351
	v_sub_f32_e32 v61, v106, v15
	v_exp_f32_e32 v62, v61
	s_nop 0
	v_mul_f32_e32 v48, v48, v62
	v_pk_mul_f32 v[46:47], v[46:47], v[62:63] op_sel_hi:[1,0]
	v_pk_mul_f32 v[44:45], v[44:45], v[62:63] op_sel_hi:[1,0]
	v_pk_mul_f32 v[42:43], v[42:43], v[62:63] op_sel_hi:[1,0]
	v_pk_mul_f32 v[40:41], v[40:41], v[62:63] op_sel_hi:[1,0]
	v_pk_mul_f32 v[38:39], v[38:39], v[62:63] op_sel_hi:[1,0]
	v_pk_mul_f32 v[36:37], v[36:37], v[62:63] op_sel_hi:[1,0]
	v_pk_mul_f32 v[34:35], v[34:35], v[62:63] op_sel_hi:[1,0]
	v_pk_mul_f32 v[32:33], v[32:33], v[62:63] op_sel_hi:[1,0]
	v_pk_mul_f32 v[30:31], v[30:31], v[62:63] op_sel_hi:[1,0]
	v_pk_mul_f32 v[28:29], v[28:29], v[62:63] op_sel_hi:[1,0]
	v_pk_mul_f32 v[26:27], v[26:27], v[62:63] op_sel_hi:[1,0]
	v_pk_mul_f32 v[24:25], v[24:25], v[62:63] op_sel_hi:[1,0]
	v_pk_mul_f32 v[22:23], v[22:23], v[62:63] op_sel_hi:[1,0]
	v_pk_mul_f32 v[20:21], v[20:21], v[62:63] op_sel_hi:[1,0]
	v_pk_mul_f32 v[18:19], v[18:19], v[62:63] op_sel_hi:[1,0]
	v_pk_mul_f32 v[16:17], v[16:17], v[62:63] op_sel_hi:[1,0]
	s_branch .LBB0_352

; #define MFMA32(a, b, c) __builtin_amdgcn_mfma_f32_32x32x16_bf16((a), (b), (c), 0, 0, 0)
; template <int MODE, bool UNI>
; DI void attn_compute(const bf16x8 (&qf)[4], const bf16x8 (&kf)[4], const bf16x8 (&vf)[2][2], int kt, int d00, const float* lut, float ubias, AttnSt& st,
;                      unsigned W, int win, int dmask, bool lane_sel) {
;     ...
;         for (int i = 0; i < 16; ++i) { const int ci = 16 * (i >> 3) + (i & 7); bia[i] = (MODE == 4) ? lb[16 * (23 - ci)] : lb[23 - ci]; }
;     }
;     f32x16 sx;
; #pragma unroll
;     for (int i = 0; i < 16; ++i) sx[i] = 0.f;
; #pragma unroll
;     for (int ks = 0; ks < 4; ++ks) sx = MFMA32(kf[ks], qf[ks], sx);
;     asm volatile("s_waitcnt lgkmcnt(0)" ::: "memory");
;     float sv[16]; float mx = NEGF;
; #pragma unroll
;     for (int i = 0; i < 16; ++i) {
;         const int ci = 16 * (i >> 3) + (i & 7);
;         const int dist = d0 - ci;
;         bool v;
;         if (MODE == 0) v = ((W >> ci) & 1u) != 0u;
;         else if (MODE == 1) v = ((unsigned)dist <= (unsigned)win) && ((dist & dmask) == 0);
;         else if (MODE == 2) v = lane_sel;
;         else v = dist >= 0;
;         const float bias = UNI ? ubias : bia[i];
;         float s = fmaf(sx[i], SC2, bias);
;         if (MODE == 0) { const unsigned t = (unsigned)__builtin_amdgcn_sbfe((int)W, ci, 1);
;             s = __uint_as_float((__float_as_uint(s) & t) | (__float_as_uint(NEGF) & ~t)); }
;         else s = v ? s : NEGF;
;         sv[i] = s; mx = fmaxf(mx, s);
;     }
;     mx = fmaxf(mx, __shfl_xor(mx, 32));
;     const float mnew = fmaxf(st.m, mx);
;     const float msafe = (mnew > -1e29f) ? mnew : 0.f;
;     if (__ballot(mnew > st.m) != 0ull) {
;         const float alpha = __builtin_amdgcn_exp2f(st.m - msafe);
;         st.l *= alpha; st.m = mnew;
; #pragma unroll
;         for (int i = 0; i < 16; ++i) { st.o0[i] *= alpha; st.o1[i] *= alpha; }
;     }
.LBB0_361:
	s_waitcnt lgkmcnt(0)
	v_mfma_f32_32x32x16_bf16 v[50:65], v[50:53], v[70:73], 0
	v_cmp_lt_i32_e32 vcc, -1, v14
	v_mfma_f32_32x32x16_bf16 v[50:65], v[90:93], v[66:69], v[50:65]
	v_mfma_f32_32x32x16_bf16 v[50:65], v[94:97], v[78:81], v[50:65]
	ds_read2_b32 v[90:91], v15 offset0:22 offset1:23
	ds_read2_b32 v[92:93], v15 offset0:20 offset1:21
	ds_read2_b32 v[94:95], v15 offset0:18 offset1:19
	ds_read2_b32 v[96:97], v15 offset0:16 offset1:17
	ds_read2_b32 v[104:105], v15 offset0:6 offset1:7
	ds_read2_b32 v[106:107], v15 offset0:4 offset1:5
	ds_read2_b32 v[108:109], v15 offset0:2 offset1:3
	ds_read2_b32 v[110:111], v15 offset1:1
	v_mfma_f32_32x32x16_bf16 v[50:65], v[86:89], v[74:77], v[50:65]
	s_waitcnt lgkmcnt(0)
	s_nop 10
	v_fmamk_f32 v49, v50, 0x3e38aa3b, v91
	v_fmac_f32_e32 v90, 0x3e38aa3b, v51
	v_fmamk_f32 v51, v54, 0x3e38aa3b, v95
	v_cndmask_b32_e32 v54, v239, v49, vcc
	v_cmp_lt_i32_e32 vcc, 0, v14
	v_fmamk_f32 v50, v52, 0x3e38aa3b, v93
	v_fmac_f32_e32 v94, 0x3e38aa3b, v55
	v_cndmask_b32_e32 v55, v239, v90, vcc
	v_cmp_lt_i32_e32 vcc, 1, v14
	v_fmac_f32_e32 v92, 0x3e38aa3b, v53
	v_fmamk_f32 v53, v56, 0x3e38aa3b, v97
	v_cndmask_b32_e32 v56, v239, v50, vcc
	v_cmp_lt_i32_e32 vcc, 2, v14
	v_fmac_f32_e32 v96, 0x3e38aa3b, v57
	v_fmac_f32_e32 v104, 0x3e38aa3b, v59
	v_cndmask_b32_e32 v50, v239, v92, vcc
	v_cmp_lt_i32_e32 vcc, 3, v14
	v_max3_f32 v49, v54, s30, v55
	v_max3_f32 v49, v49, v56, v50
	v_cndmask_b32_e32 v51, v239, v51, vcc
	v_cmp_lt_i32_e32 vcc, 4, v14
	v_fmac_f32_e32 v106, 0x3e38aa3b, v61
	v_fmac_f32_e32 v108, 0x3e38aa3b, v63
	v_cndmask_b32_e32 v52, v239, v94, vcc
	v_cmp_lt_i32_e32 vcc, 5, v14
	v_max3_f32 v49, v49, v51, v52
	v_fmac_f32_e32 v110, 0x3e38aa3b, v65
	v_cndmask_b32_e32 v86, v239, v53, vcc
	v_cmp_lt_i32_e32 vcc, 6, v14
	v_fmamk_f32 v53, v58, 0x3e38aa3b, v105
	s_nop 0
	v_cndmask_b32_e32 v87, v239, v96, vcc
	v_cmp_lt_i32_e32 vcc, 15, v14
	v_max3_f32 v49, v49, v86, v87
	s_nop 0
	v_cndmask_b32_e32 v58, v239, v53, vcc
	v_cmp_lt_i32_e32 vcc, 16, v14
	v_fmamk_f32 v53, v60, 0x3e38aa3b, v107
	s_nop 0
	v_cndmask_b32_e32 v59, v239, v104, vcc
	v_cmp_lt_i32_e32 vcc, 17, v14
	v_max3_f32 v49, v49, v58, v59
	s_nop 0
	v_cndmask_b32_e32 v60, v239, v53, vcc
	v_cmp_lt_i32_e32 vcc, 18, v14
	v_fmamk_f32 v53, v62, 0x3e38aa3b, v109
	s_nop 0
	v_cndmask_b32_e32 v61, v239, v106, vcc
	v_cmp_lt_i32_e32 vcc, 19, v14
	v_max3_f32 v49, v49, v60, v61
	s_nop 0
	v_cndmask_b32_e32 v62, v239, v53, vcc
	v_cmp_lt_i32_e32 vcc, 20, v14
	v_fmamk_f32 v53, v64, 0x3e38aa3b, v111
	s_nop 0
	v_cndmask_b32_e32 v63, v239, v108, vcc
	v_cmp_lt_i32_e32 vcc, 21, v14
	v_max3_f32 v49, v49, v62, v63
	s_nop 0
	v_cndmask_b32_e32 v64, v239, v53, vcc
	v_cmp_lt_i32_e32 vcc, 22, v14
	s_nop 1
	v_cndmask_b32_e32 v53, v239, v110, vcc
	v_max3_f32 v49, v49, v64, v53
	v_mov_b32_e32 v57, v49
	s_nop 1
	v_permlane32_swap_b32_e32 v57, v49
	s_waitcnt lgkmcnt(0)
	v_max3_f32 v49, v0, v49, v57
	v_cmp_lt_f32_e32 vcc, s12, v49
	s_nop 1
	v_cndmask_b32_e32 v57, 0, v49, vcc
	v_cmp_gt_f32_e32 vcc, v49, v0
	s_cbranch_vccz .LBB0_363
	v_sub_f32_e32 v0, v0, v57
	v_exp_f32_e32 v0, v0
	s_nop 0
	v_mul_f32_e32 v48, v48, v0
	v_pk_mul_f32 v[46:47], v[46:47], v[0:1] op_sel_hi:[1,0]
	v_pk_mul_f32 v[44:45], v[44:45], v[0:1] op_sel_hi:[1,0]
	v_pk_mul_f32 v[42:43], v[42:43], v[0:1] op_sel_hi:[1,0]
	v_pk_mul_f32 v[40:41], v[40:41], v[0:1] op_sel_hi:[1,0]
	v_pk_mul_f32 v[38:39], v[38:39], v[0:1] op_sel_hi:[1,0]
	v_pk_mul_f32 v[36:37], v[36:37], v[0:1] op_sel_hi:[1,0]
	v_pk_mul_f32 v[34:35], v[34:35], v[0:1] op_sel_hi:[1,0]
	v_pk_mul_f32 v[32:33], v[32:33], v[0:1] op_sel_hi:[1,0]
	v_pk_mul_f32 v[30:31], v[30:31], v[0:1] op_sel_hi:[1,0]
	v_pk_mul_f32 v[28:29], v[28:29], v[0:1] op_sel_hi:[1,0]
	v_pk_mul_f32 v[26:27], v[26:27], v[0:1] op_sel_hi:[1,0]
	v_pk_mul_f32 v[24:25], v[24:25], v[0:1] op_sel_hi:[1,0]
	v_pk_mul_f32 v[22:23], v[22:23], v[0:1] op_sel_hi:[1,0]
	v_pk_mul_f32 v[20:21], v[20:21], v[0:1] op_sel_hi:[1,0]
	v_pk_mul_f32 v[18:19], v[18:19], v[0:1] op_sel_hi:[1,0]
	v_pk_mul_f32 v[16:17], v[16:17], v[0:1] op_sel_hi:[1,0]
	s_branch .LBB0_364
